# k44 + strategy 4: one static s_setprio 1 for waves 4-7 around the neighbourhood-attention loops (reset at loop exit)
# baseline (speedup 1.0000x reference)
; __device__ __forceinline__ int v_rd_base(int lane) { return ((lane & 3) << 3) | (((lane >> 2) & 3) << 6) | (((lane >> 4) & 1) << 5) | (((lane >> 5) & 1) << 8); }
; #define NPUB() do { asm volatile("s_waitcnt vmcnt(0)" ::: "memory"); __syncthreads(); } while (0)
; template <bool NA> __device__ __forceinline__ void unit_body_v128(const Unit& U, char* lds) {
;   int tid = threadIdx.x; asm volatile("" : "+v"(tid)); const int wid = __builtin_amdgcn_readfirstlane(tid >> 6), lane = tid & 63, r32 = lane & 31, hi = lane >> 5;
;   char* V_lds = lds; char* K_lds = lds + 2 * DA_VB;
;   float* ws = (float*)(lds + DA_WS_OFF) + wid * 64; float* li_l = ws; float* al_l = ws + 32;
;   float m_reg = -1e30f, l_reg = 0; f32x16 o[4] = {}; bf16x8 qr[8];
;   const bf16_t* Qw = U.Q + (long)(wid * QBLK + r32) * LDP + hi * 8;
; #pragma unroll
;   for (int d0 = 0; d0 < 8; ++d0) qr[d0] = ld8(Qw + d0 * 16);
;   const int vb0 = (int)(uintptr_t)V_lds + v_rd_base(lane);
;   const int ka0 = (int)(uintptr_t)K_lds + KSWZ(r32, hi * 16);
;   unsigned koff[2], voff[2];
; #pragma unroll
;   for (int i = 0; i < 2; ++i) { const int ob = (2 * wid + i) * 1024 + lane * 16;
;     { const int row = ob >> 8, cpos = (ob >> 4) & 15, c = cpos ^ (row & 7); koff[i] = (unsigned)(row * LDP + c * 8); }
;     { const int st = ob >> 9, kk = (st >> 2) * 8 + ((ob >> 6) & 7), c = (st & 3) * 32 + ((ob >> 1) & 31), k = (kk & ~0xC) | ((kk & 4) << 1) | ((kk & 8) >> 1); voff[i] = (unsigned)(k * LDP + c); } }
;   typedef __attribute__((address_space(3))) unsigned lds_u32;
;   const int nsplit = U.nsplit, base1 = U.base1;
;     ...
;   const int NT = U.nt;
;   NDMA(0, 0); NPUB();
.LBB0_380:
	v_mov_b32_e32 v6, v210
	v_mov_b64_e32 v[2:3], s[58:59]
	v_readfirstlane_b32 s9, v6
	s_and_b32 s4, s9, 0x3fffffc0
	s_ashr_i32 s26, s9, 6
	s_lshl_b32 s4, s4, 2
	v_and_b32_e32 v140, 31, v6
	s_add_i32 s4, s4, 0
	s_lshl_b32 s66, s26, 5
	v_bfe_u32 v139, v6, 5, 1
	s_add_i32 s27, s4, 0x18000
	v_or_b32_e32 v0, s66, v140
	s_add_i32 s33, 0, 0x10000
	v_mad_i64_i32 v[2:3], s[4:5], v0, s96, v[2:3]
	v_lshlrev_b32_e32 v4, 4, v139
	v_mov_b32_e32 v5, v1
	s_cmp_lg_u32 s33, -1
	v_lshl_add_u64 v[2:3], v[2:3], 0, v[4:5]
	s_cselect_b32 s4, s33, 0
	s_lshl_b32 s29, s26, 11
	global_load_dwordx4 v[98:101], v[2:3], off
	global_load_dwordx4 v[102:105], v[2:3], off offset:32
	global_load_dwordx4 v[106:109], v[2:3], off offset:64
	global_load_dwordx4 v[110:113], v[2:3], off offset:96
	global_load_dwordx4 v[114:117], v[2:3], off offset:128
	global_load_dwordx4 v[118:121], v[2:3], off offset:160
	global_load_dwordx4 v[122:125], v[2:3], off offset:192
	global_load_dwordx4 v[126:129], v[2:3], off offset:224
	s_ashr_i32 s5, s29, 8
	v_lshrrev_b32_e32 v3, 1, v6
	v_bfe_u32 v0, v6, 2, 2
	s_and_b32 s26, s5, 0xfffff0
	v_and_b32_e32 v3, 8, v3
	v_and_b32_e32 v7, 63, v6
	s_lshr_b32 s5, s5, 1
	v_or3_b32 v0, v3, v0, s26
	v_lshlrev_b32_e32 v9, 4, v7
	v_and_or_b32 v0, s5, 4, v0
	v_mul_i32_i24_e32 v3, 0x1800, v0
	v_or_b32_e32 v0, s29, v9
	v_and_b32_e32 v2, 15, v6
	v_ashrrev_i32_e32 v0, 8, v0
	v_lshlrev_b32_e32 v5, 3, v7
	v_bitop3_b32 v10, v0, v2, 15 bitop3:0x6c
	v_mul_i32_i24_e32 v0, 0x1800, v0
	v_and_b32_e32 v8, 24, v5
	v_lshl_or_b32 v0, v10, 3, v0
	v_and_b32_e32 v10, 32, v6
	v_or3_b32 v130, v8, v10, v3
	v_or_b32_e32 v10, 0x400, v9
	v_or_b32_e32 v11, s29, v10
	v_ashrrev_i32_e32 v11, 8, v11
	v_bitop3_b32 v2, v11, v2, 15 bitop3:0x6c
	v_mul_i32_i24_e32 v11, 0x1800, v11
	v_lshl_or_b32 v132, v2, 3, v11
	v_lshrrev_b32_e32 v2, 4, v10
	s_cmp_lg_u32 0, -1
	v_and_b32_e32 v2, 0x60, v2
	s_cselect_b32 s26, 0, 0
	s_add_i32 s67, s33, s29
	v_or3_b32 v134, v8, v2, v3
	v_lshl_add_u64 v[2:3], v[0:1], 1, s[46:47]
	s_mov_b32 m0, s67
	v_mov_b32_e32 v131, v1
	s_add_i32 s30, s29, 0
	s_or_b32 s31, s29, 0x400
	global_load_lds_dwordx4 v[2:3], off
	v_lshl_add_u64 v[2:3], v[130:131], 1, s[22:23]
	s_mov_b32 m0, s30
	v_mov_b32_e32 v133, v1
	s_add_i32 s33, s33, s31
	global_load_lds_dwordx4 v[2:3], off
	v_lshl_add_u64 v[2:3], v[132:133], 1, s[46:47]
	s_mov_b32 m0, s33
	v_mov_b32_e32 v135, v1
	s_add_i32 s35, s30, 0x400
	global_load_lds_dwordx4 v[2:3], off
	v_lshl_add_u64 v[2:3], v[134:135], 1, s[22:23]
	s_mov_b32 m0, s35
	s_ashr_i32 s9, s9, 7
	global_load_lds_dwordx4 v[2:3], off
	v_lshlrev_b32_e32 v2, 1, v6
	v_and_b32_e32 v2, 32, v2
	v_and_or_b32 v2, v9, s97, v2
	v_and_b32_e32 v3, 0x100, v5
	v_bitop3_b32 v5, v139, v6, 15 bitop3:0x78
	v_or3_b32 v2, v2, v3, v8
	v_lshlrev_b32_e32 v3, 8, v140
	v_lshlrev_b32_e32 v5, 4, v5
	v_add_u32_e32 v142, s26, v2
	v_add3_u32 v143, v3, s4, v5
	v_and_or_b32 v3, s66, 32, v140
	s_add_i32 s26, s26, 0x8000
	v_add_u32_e32 v152, s26, v2
	v_lshl_or_b32 v2, v3, 8, v4
	v_mov_b32_e32 v3, v1
	s_add_i32 s9, s9, s3
	s_sub_i32 s26, s8, s24
	v_lshl_add_u64 v[136:137], s[6:7], 0, v[2:3]
	v_med3_i32 v2, s9, 4, v232
	s_sub_i32 s9, s26, s9
	s_add_i32 s6, s9, 7
	s_ashr_i32 s7, s6, 31
	s_lshl_b64 s[68:69], s[6:7], 12
	s_lshl_b32 s6, s24, 6
	s_waitcnt vmcnt(0)
	s_sub_i32 s8, s25, s6
	s_add_i32 s6, s9, 8
	v_mov_b32_e32 v16, v1
	v_mov_b32_e32 v17, v1
	v_cmp_gt_u32_e64 s[4:5], 32, v7
	v_lshl_add_u32 v146, v140, 2, s27
	v_add_u32_e32 v138, s27, v4
	v_readfirstlane_b32 s27, v2
	s_ashr_i32 s7, s6, 31
	v_mov_b32_e32 v2, v1
	v_mov_b32_e32 v4, v1
	v_mov_b32_e32 v5, v1
	v_mov_b32_e32 v6, v1
	v_mov_b32_e32 v7, v1
	v_mov_b32_e32 v8, v1
	v_mov_b32_e32 v9, v1
	v_mov_b32_e32 v10, v1
	v_mov_b32_e32 v11, v1
	v_mov_b32_e32 v12, v1
	v_mov_b32_e32 v13, v1
	v_mov_b32_e32 v14, v1
	v_mov_b32_e32 v15, v1
	v_mov_b64_e32 v[64:65], v[16:17]
	v_mov_b64_e32 v[48:49], v[16:17]
	v_mov_b64_e32 v[32:33], v[16:17]
	s_mov_b32 s90, 2
	v_lshlrev_b32_e32 v141, 2, v139
	v_xor_b32_e32 v144, 32, v143
	v_xor_b32_e32 v145, 64, v143
	v_xor_b32_e32 v147, 0x60, v143
	s_movk_i32 s91, 0x80
	v_xor_b32_e32 v148, 0x80, v143
	v_xor_b32_e32 v149, 0xa0, v143
	v_xor_b32_e32 v150, 0xc0, v143
	v_xor_b32_e32 v151, 0xe0, v143
	s_add_i32 s3, s27, -4
	s_add_i32 s27, s27, 4
	s_lshl_b64 s[80:81], s[6:7], 12
	v_mov_b32_e32 v153, 0
	v_mov_b32_e32 v155, 0xf149f2ca
	v_mov_b64_e32 v[62:63], v[14:15]
	v_mov_b64_e32 v[60:61], v[12:13]
	v_mov_b64_e32 v[58:59], v[10:11]
	v_mov_b64_e32 v[56:57], v[8:9]
	v_mov_b64_e32 v[54:55], v[6:7]
	v_mov_b64_e32 v[52:53], v[4:5]
	v_mov_b64_e32 v[50:51], v[2:3]
	v_mov_b64_e32 v[46:47], v[14:15]
	v_mov_b64_e32 v[44:45], v[12:13]
	v_mov_b64_e32 v[42:43], v[10:11]
	v_mov_b64_e32 v[40:41], v[8:9]
	v_mov_b64_e32 v[38:39], v[6:7]
	v_mov_b64_e32 v[36:37], v[4:5]
	v_mov_b64_e32 v[34:35], v[2:3]
	v_mov_b64_e32 v[30:31], v[14:15]
	v_mov_b64_e32 v[28:29], v[12:13]
	v_mov_b64_e32 v[26:27], v[10:11]
	v_mov_b64_e32 v[24:25], v[8:9]
	v_mov_b64_e32 v[22:23], v[6:7]
	v_mov_b64_e32 v[20:21], v[4:5]
	v_mov_b64_e32 v[18:19], v[2:3]
	s_waitcnt vmcnt(0) lgkmcnt(0)
	s_barrier
	s_cmp_lt_u32 s29, 0x2000
	s_cbranch_scc1 .Lna_l0_noprio
	s_setprio 1
.Lna_l0_noprio:
	s_branch .LBB0_383
.LBB0_381:
	s_or_b64 exec, exec, s[84:85]
	s_waitcnt lgkmcnt(0)
	ds_read_b128 v[160:163], v138 offset:224
	ds_read_b128 v[164:167], v138 offset:192
	ds_read_b128 v[168:171], v138 offset:160
	ds_read_b128 v[172:175], v138 offset:128
	s_waitcnt lgkmcnt(0)
	v_pk_mul_f32 v[16:17], v[16:17], v[162:163]
	v_pk_mul_f32 v[12:13], v[12:13], v[166:167]
	v_pk_mul_f32 v[8:9], v[8:9], v[170:171]
	v_pk_mul_f32 v[4:5], v[4:5], v[174:175]
	v_pk_mul_f32 v[14:15], v[14:15], v[160:161]
	v_pk_mul_f32 v[10:11], v[10:11], v[164:165]
	v_pk_mul_f32 v[6:7], v[6:7], v[168:169]
	v_pk_mul_f32 v[2:3], v[2:3], v[172:173]
	v_pk_mul_f32 v[64:65], v[64:65], v[162:163]
	v_pk_mul_f32 v[60:61], v[60:61], v[166:167]
	v_pk_mul_f32 v[56:57], v[56:57], v[170:171]
	v_pk_mul_f32 v[52:53], v[52:53], v[174:175]
	v_pk_mul_f32 v[62:63], v[62:63], v[160:161]
	v_pk_mul_f32 v[58:59], v[58:59], v[164:165]
	v_pk_mul_f32 v[54:55], v[54:55], v[168:169]
	v_pk_mul_f32 v[50:51], v[50:51], v[172:173]
	v_pk_mul_f32 v[48:49], v[48:49], v[162:163]
	v_pk_mul_f32 v[44:45], v[44:45], v[166:167]
	v_pk_mul_f32 v[40:41], v[40:41], v[170:171]
	v_pk_mul_f32 v[36:37], v[36:37], v[174:175]
	v_pk_mul_f32 v[46:47], v[46:47], v[160:161]
	v_pk_mul_f32 v[42:43], v[42:43], v[164:165]
	v_pk_mul_f32 v[38:39], v[38:39], v[168:169]
	v_pk_mul_f32 v[34:35], v[34:35], v[172:173]
	v_pk_mul_f32 v[32:33], v[32:33], v[162:163]
	v_pk_mul_f32 v[28:29], v[28:29], v[166:167]
	v_pk_mul_f32 v[24:25], v[24:25], v[170:171]
	v_pk_mul_f32 v[20:21], v[20:21], v[174:175]
	v_pk_mul_f32 v[30:31], v[30:31], v[160:161]
	v_pk_mul_f32 v[26:27], v[26:27], v[164:165]
	v_pk_mul_f32 v[22:23], v[22:23], v[168:169]
	v_pk_mul_f32 v[18:19], v[18:19], v[172:173]

; __device__ __forceinline__ int crow(int r, int hi) { return (r & 3) + 8 * (r >> 2) + 4 * hi; }
; template <bool NA> __device__ __forceinline__ void unit_body_v128(const Unit& U, char* lds) {
;     ...
;   if (hi == 0) li_l[r32] = l_reg; asm volatile("s_waitcnt lgkmcnt(0)" ::: "memory");
;   if (U.Of) {
;     float* Ow = U.Of + (long)(wid * QBLK) * LDO;
; #pragma unroll
;     for (int r = 0; r < 16; ++r) { const int orow = crow(r, hi); const float rl = __builtin_amdgcn_rcpf(li_l[orow]);
; #pragma unroll
;       for (int d0 = 0; d0 < 4; ++d0) Ow[(long)orow * LDO + d0 * 32 + r32] = o[d0][r] * rl; }
.LBB0_399:
	s_setprio 0
	s_and_saveexec_b64 s[6:7], s[4:5]
	ds_write_b32 v146, v153
	s_or_b64 exec, exec, s[6:7]
	s_waitcnt lgkmcnt(0)
	ds_read_b32 v0, v138
	s_ashr_i32 s67, s66, 31
	s_cmp_eq_u64 s[18:19], 0
	s_waitcnt lgkmcnt(0)
	v_rcp_f32_e32 v0, v0
	s_nop 0
	v_mul_f32_e32 v68, v2, v0
	v_mul_f32_e32 v50, v50, v0
	v_mul_f32_e32 v34, v34, v0
	v_mul_f32_e32 v2, v18, v0
	s_cbranch_scc1 .LBB0_425
; __device__ __forceinline__ int crow(int r, int hi) { return (r & 3) + 8 * (r >> 2) + 4 * hi; }
; template <bool NA> __device__ __forceinline__ void unit_body_v128(const Unit& U, char* lds) {
;     ...
;   if (U.Of) {
;     float* Ow = U.Of + (long)(wid * QBLK) * LDO;
; #pragma unroll
;     for (int r = 0; r < 16; ++r) { const int orow = crow(r, hi); const float rl = __builtin_amdgcn_rcpf(li_l[orow]);
; #pragma unroll
;       for (int d0 = 0; d0 < 4; ++d0) Ow[(long)orow * LDO + d0 * 32 + r32] = o[d0][r] * rl; }
	ds_read2_b32 v[72:73], v138 offset0:1 offset1:2
	s_lshl_b64 s[4:5], s[66:67], 13
	s_add_u32 s4, s18, s4
	s_addc_u32 s5, s19, s5
	v_lshlrev_b32_e32 v0, 2, v140
	s_waitcnt lgkmcnt(0)
	v_rcp_f32_e32 v69, v72
	v_lshl_add_u64 v[66:67], s[4:5], 0, v[0:1]
	v_lshlrev_b32_e32 v0, 15, v139
	v_lshlrev_b32_e32 v80, 13, v141
	v_lshl_add_u64 v[70:71], v[66:67], 0, v[0:1]
	v_or_b32_e32 v0, 0x2000, v80
	global_store_dword v[70:71], v68, off
	global_store_dword v[70:71], v50, off offset:128
	global_store_dword v[70:71], v34, off offset:256
	global_store_dword v[70:71], v2, off offset:384
	v_lshl_add_u64 v[70:71], v[66:67], 0, v[0:1]
	v_mul_f32_e32 v0, v3, v69
	global_store_dword v[70:71], v0, off
	v_mul_f32_e32 v0, v51, v69
	global_store_dword v[70:71], v0, off offset:128
	v_mul_f32_e32 v0, v35, v69
	global_store_dword v[70:71], v0, off offset:256
	v_mul_f32_e32 v0, v19, v69
	v_rcp_f32_e32 v69, v73
	ds_read_b32 v18, v138 offset:12
	global_store_dword v[70:71], v0, off offset:384
	v_or_b32_e32 v0, 0x4000, v80
	v_lshl_add_u64 v[70:71], v[66:67], 0, v[0:1]
	v_mul_f32_e32 v0, v4, v69
	global_store_dword v[70:71], v0, off
	v_mul_f32_e32 v0, v52, v69
	global_store_dword v[70:71], v0, off offset:128
	v_mul_f32_e32 v0, v36, v69
	global_store_dword v[70:71], v0, off offset:256
	v_mul_f32_e32 v0, v20, v69
	global_store_dword v[70:71], v0, off offset:384
	ds_read_b128 v[70:73], v138 offset:32
	s_waitcnt lgkmcnt(1)
	v_rcp_f32_e32 v18, v18
	v_or_b32_e32 v0, 0x6000, v80
	v_lshl_add_u64 v[78:79], v[66:67], 0, v[0:1]
	ds_read_b128 v[74:77], v138 offset:64
	v_mul_f32_e32 v0, v5, v18
	global_store_dword v[78:79], v0, off
	v_mul_f32_e32 v0, v53, v18
	global_store_dword v[78:79], v0, off offset:128
	v_mul_f32_e32 v0, v37, v18
	global_store_dword v[78:79], v0, off offset:256
	v_mul_f32_e32 v0, v21, v18
	s_waitcnt lgkmcnt(1)
	v_rcp_f32_e32 v18, v70
	global_store_dword v[78:79], v0, off offset:384
	v_or_b32_e32 v0, 0x10000, v80
	v_lshl_add_u64 v[78:79], v[66:67], 0, v[0:1]
	v_mul_f32_e32 v0, v6, v18
	global_store_dword v[78:79], v0, off
	v_mul_f32_e32 v0, v54, v18
	global_store_dword v[78:79], v0, off offset:128
	v_mul_f32_e32 v0, v38, v18
	global_store_dword v[78:79], v0, off offset:256
	v_mul_f32_e32 v0, v22, v18
	v_rcp_f32_e32 v18, v71
	global_store_dword v[78:79], v0, off offset:384
	v_or_b32_e32 v0, 0x12000, v80
	v_lshl_add_u64 v[70:71], v[66:67], 0, v[0:1]
	v_mul_f32_e32 v0, v7, v18
	global_store_dword v[70:71], v0, off
	v_mul_f32_e32 v0, v55, v18
	global_store_dword v[70:71], v0, off offset:128
	v_mul_f32_e32 v0, v39, v18
	global_store_dword v[70:71], v0, off offset:256
	v_mul_f32_e32 v0, v23, v18
	v_rcp_f32_e32 v18, v72
	global_store_dword v[70:71], v0, off offset:384
	v_or_b32_e32 v0, 0x14000, v80
	v_lshl_add_u64 v[70:71], v[66:67], 0, v[0:1]
	v_mul_f32_e32 v0, v8, v18
	global_store_dword v[70:71], v0, off
	v_mul_f32_e32 v0, v56, v18
	global_store_dword v[70:71], v0, off offset:128
	v_mul_f32_e32 v0, v40, v18
	global_store_dword v[70:71], v0, off offset:256
	v_mul_f32_e32 v0, v24, v18
	v_rcp_f32_e32 v18, v73
	global_store_dword v[70:71], v0, off offset:384
	v_or_b32_e32 v0, 0x16000, v80
	v_lshl_add_u64 v[70:71], v[66:67], 0, v[0:1]
	v_mul_f32_e32 v0, v9, v18
	global_store_dword v[70:71], v0, off
	v_mul_f32_e32 v0, v57, v18
	global_store_dword v[70:71], v0, off offset:128
	v_mul_f32_e32 v0, v41, v18
	global_store_dword v[70:71], v0, off offset:256
	v_mul_f32_e32 v0, v25, v18
	s_waitcnt lgkmcnt(0)
	v_rcp_f32_e32 v18, v74
	global_store_dword v[70:71], v0, off offset:384
	v_or_b32_e32 v0, 0x20000, v80
	v_lshl_add_u64 v[70:71], v[66:67], 0, v[0:1]
	v_mul_f32_e32 v0, v10, v18
	global_store_dword v[70:71], v0, off
	v_mul_f32_e32 v0, v58, v18
	global_store_dword v[70:71], v0, off offset:128
	v_mul_f32_e32 v0, v42, v18
	global_store_dword v[70:71], v0, off offset:256
	v_mul_f32_e32 v0, v26, v18
	v_rcp_f32_e32 v18, v75
	global_store_dword v[70:71], v0, off offset:384
	v_or_b32_e32 v0, 0x22000, v80
	v_lshl_add_u64 v[70:71], v[66:67], 0, v[0:1]
	v_mul_f32_e32 v0, v11, v18
	global_store_dword v[70:71], v0, off
	v_mul_f32_e32 v0, v59, v18
	global_store_dword v[70:71], v0, off offset:128
	v_mul_f32_e32 v0, v43, v18
	global_store_dword v[70:71], v0, off offset:256
	v_mul_f32_e32 v0, v27, v18
	v_rcp_f32_e32 v18, v76
	global_store_dword v[70:71], v0, off offset:384
	v_or_b32_e32 v0, 0x24000, v80
	v_lshl_add_u64 v[70:71], v[66:67], 0, v[0:1]
	v_mul_f32_e32 v0, v12, v18
	global_store_dword v[70:71], v0, off
	v_mul_f32_e32 v0, v60, v18
	global_store_dword v[70:71], v0, off offset:128
	v_mul_f32_e32 v0, v44, v18
	global_store_dword v[70:71], v0, off offset:256
	v_mul_f32_e32 v0, v28, v18
	v_rcp_f32_e32 v18, v77
	global_store_dword v[70:71], v0, off offset:384
	ds_read_b128 v[70:73], v138 offset:96
	v_or_b32_e32 v0, 0x26000, v80
	v_lshl_add_u64 v[74:75], v[66:67], 0, v[0:1]
	v_mul_f32_e32 v0, v13, v18
	global_store_dword v[74:75], v0, off
	v_mul_f32_e32 v0, v61, v18
	global_store_dword v[74:75], v0, off offset:128
	v_mul_f32_e32 v0, v45, v18
	global_store_dword v[74:75], v0, off offset:256
	v_mul_f32_e32 v0, v29, v18
	s_waitcnt lgkmcnt(0)
	v_rcp_f32_e32 v18, v70
	global_store_dword v[74:75], v0, off offset:384
	v_or_b32_e32 v0, 0x30000, v80
	v_lshl_add_u64 v[74:75], v[66:67], 0, v[0:1]
	v_mul_f32_e32 v0, v14, v18
	global_store_dword v[74:75], v0, off
	v_mul_f32_e32 v0, v62, v18
	global_store_dword v[74:75], v0, off offset:128
	v_mul_f32_e32 v0, v46, v18
	global_store_dword v[74:75], v0, off offset:256
	v_mul_f32_e32 v0, v30, v18
	v_rcp_f32_e32 v18, v71
	global_store_dword v[74:75], v0, off offset:384
	v_or_b32_e32 v0, 0x32000, v80
	v_lshl_add_u64 v[70:71], v[66:67], 0, v[0:1]
	v_mul_f32_e32 v0, v15, v18
	global_store_dword v[70:71], v0, off
	v_mul_f32_e32 v0, v63, v18
	global_store_dword v[70:71], v0, off offset:128
	v_mul_f32_e32 v0, v47, v18
	global_store_dword v[70:71], v0, off offset:256
	v_mul_f32_e32 v0, v31, v18
	v_rcp_f32_e32 v18, v72
	global_store_dword v[70:71], v0, off offset:384
	v_or_b32_e32 v0, 0x34000, v80
	v_lshl_add_u64 v[70:71], v[66:67], 0, v[0:1]
	v_mul_f32_e32 v0, v16, v18
	global_store_dword v[70:71], v0, off
	v_mul_f32_e32 v0, v64, v18
	global_store_dword v[70:71], v0, off offset:128
	v_mul_f32_e32 v0, v48, v18
	global_store_dword v[70:71], v0, off offset:256
	v_mul_f32_e32 v0, v32, v18
	v_rcp_f32_e32 v18, v73
	global_store_dword v[70:71], v0, off offset:384
	v_or_b32_e32 v0, 0x36000, v80
	v_lshl_add_u64 v[66:67], v[66:67], 0, v[0:1]
	v_mul_f32_e32 v0, v17, v18
	global_store_dword v[66:67], v0, off
	v_mul_f32_e32 v0, v65, v18
	global_store_dword v[66:67], v0, off offset:128
	v_mul_f32_e32 v0, v49, v18
	global_store_dword v[66:67], v0, off offset:256
	v_mul_f32_e32 v0, v33, v18
	global_store_dword v[66:67], v0, off offset:384
	s_cbranch_execnz .LBB0_404

; __device__ __forceinline__ int v_rd_base(int lane) { return ((lane & 3) << 3) | (((lane >> 2) & 3) << 6) | (((lane >> 4) & 1) << 5) | (((lane >> 5) & 1) << 8); }
; #define NPUB() do { asm volatile("s_waitcnt vmcnt(0)" ::: "memory"); __syncthreads(); } while (0)
; template <bool NA> __device__ __forceinline__ void unit_body_v128(const Unit& U, char* lds) {
;   int tid = threadIdx.x; asm volatile("" : "+v"(tid)); const int wid = __builtin_amdgcn_readfirstlane(tid >> 6), lane = tid & 63, r32 = lane & 31, hi = lane >> 5;
;   char* V_lds = lds; char* K_lds = lds + 2 * DA_VB;
;   float* ws = (float*)(lds + DA_WS_OFF) + wid * 64; float* li_l = ws; float* al_l = ws + 32;
;   float m_reg = -1e30f, l_reg = 0; f32x16 o[4] = {}; bf16x8 qr[8];
;   const bf16_t* Qw = U.Q + (long)(wid * QBLK + r32) * LDP + hi * 8;
; #pragma unroll
;   for (int d0 = 0; d0 < 8; ++d0) qr[d0] = ld8(Qw + d0 * 16);
;   const int vb0 = (int)(uintptr_t)V_lds + v_rd_base(lane);
;   const int ka0 = (int)(uintptr_t)K_lds + KSWZ(r32, hi * 16);
;   unsigned koff[2], voff[2];
; #pragma unroll
;   for (int i = 0; i < 2; ++i) { const int ob = (2 * wid + i) * 1024 + lane * 16;
;     { const int row = ob >> 8, cpos = (ob >> 4) & 15, c = cpos ^ (row & 7); koff[i] = (unsigned)(row * LDP + c * 8); }
;     { const int st = ob >> 9, kk = (st >> 2) * 8 + ((ob >> 6) & 7), c = (st & 3) * 32 + ((ob >> 1) & 31), k = (kk & ~0xC) | ((kk & 4) << 1) | ((kk & 8) >> 1); voff[i] = (unsigned)(k * LDP + c); } }
;   typedef __attribute__((address_space(3))) unsigned lds_u32;
;   const int nsplit = U.nsplit, base1 = U.base1;
;     ...
;   const int NT = U.nt;
;   NDMA(0, 0); NPUB();
.LBB0_1410:
	v_mov_b32_e32 v6, v210
	v_mov_b64_e32 v[2:3], s[56:57]
	v_readfirstlane_b32 s5, v6
	s_and_b32 s0, s5, 0x3fffffc0
	s_ashr_i32 s4, s5, 6
	s_lshl_b32 s0, s0, 2
	v_and_b32_e32 v140, 31, v6
	s_add_i32 s0, s0, 0
	s_lshl_b32 s62, s4, 5
	s_waitcnt vmcnt(0)
	v_bfe_u32 v139, v6, 5, 1
	s_add_i32 s27, s0, 0x18000
	v_or_b32_e32 v0, s62, v140
	s_add_i32 s97, 0, 0x10000
	v_mad_i64_i32 v[2:3], s[0:1], v0, s92, v[2:3]
	v_lshlrev_b32_e32 v4, 4, v139
	v_mov_b32_e32 v5, v1
	s_cmp_lg_u32 s97, -1
	v_lshl_add_u64 v[2:3], v[2:3], 0, v[4:5]
	s_cselect_b32 s0, s97, 0
	s_lshl_b32 s29, s4, 11
	global_load_dwordx4 v[98:101], v[2:3], off
	global_load_dwordx4 v[102:105], v[2:3], off offset:32
	global_load_dwordx4 v[106:109], v[2:3], off offset:64
	global_load_dwordx4 v[110:113], v[2:3], off offset:96
	global_load_dwordx4 v[114:117], v[2:3], off offset:128
	global_load_dwordx4 v[118:121], v[2:3], off offset:160
	global_load_dwordx4 v[122:125], v[2:3], off offset:192
	global_load_dwordx4 v[126:129], v[2:3], off offset:224
	s_ashr_i32 s1, s29, 8
	v_lshrrev_b32_e32 v3, 1, v6
	v_bfe_u32 v0, v6, 2, 2
	s_and_b32 s4, s1, 0xfffff0
	v_and_b32_e32 v3, 8, v3
	v_and_b32_e32 v7, 63, v6
	s_lshr_b32 s1, s1, 1
	v_or3_b32 v0, v3, v0, s4
	v_lshlrev_b32_e32 v9, 4, v7
	v_and_or_b32 v0, s1, 4, v0
	v_mul_i32_i24_e32 v3, 0x1800, v0
	v_or_b32_e32 v0, s29, v9
	v_and_b32_e32 v2, 15, v6
	v_ashrrev_i32_e32 v0, 8, v0
	v_lshlrev_b32_e32 v5, 3, v7
	v_bitop3_b32 v10, v0, v2, 15 bitop3:0x6c
	v_mul_i32_i24_e32 v0, 0x1800, v0
	v_and_b32_e32 v8, 24, v5
	v_lshl_or_b32 v0, v10, 3, v0
	v_and_b32_e32 v10, 32, v6
	v_or3_b32 v130, v8, v10, v3
	v_or_b32_e32 v10, 0x400, v9
	v_or_b32_e32 v11, s29, v10
	v_ashrrev_i32_e32 v11, 8, v11
	v_bitop3_b32 v2, v11, v2, 15 bitop3:0x6c
	v_mul_i32_i24_e32 v11, 0x1800, v11
	v_lshl_or_b32 v132, v2, 3, v11
	v_lshrrev_b32_e32 v2, 4, v10
	s_cmp_lg_u32 0, -1
	v_and_b32_e32 v2, 0x60, v2
	s_cselect_b32 s59, 0, 0
	s_add_i32 s63, s97, s29
	v_or3_b32 v134, v8, v2, v3
	v_lshl_add_u64 v[2:3], v[0:1], 1, s[24:25]
	s_mov_b32 m0, s63
	v_mov_b32_e32 v131, v1
	s_add_i32 s30, s29, 0
	s_or_b32 s31, s29, 0x400
	global_load_lds_dwordx4 v[2:3], off
	v_lshl_add_u64 v[2:3], v[130:131], 1, s[22:23]
	s_mov_b32 m0, s30
	v_mov_b32_e32 v133, v1
	s_add_i32 s97, s97, s31
	global_load_lds_dwordx4 v[2:3], off
	v_lshl_add_u64 v[2:3], v[132:133], 1, s[24:25]
	s_mov_b32 m0, s97
	v_mov_b32_e32 v135, v1
	s_add_i32 s21, s30, 0x400
	global_load_lds_dwordx4 v[2:3], off
	v_lshl_add_u64 v[2:3], v[134:135], 1, s[22:23]
	s_mov_b32 m0, s21
	s_ashr_i32 s66, s5, 7
	global_load_lds_dwordx4 v[2:3], off
	v_lshlrev_b32_e32 v2, 1, v6
	v_and_b32_e32 v2, 32, v2
	v_and_or_b32 v2, v9, s93, v2
	v_and_b32_e32 v3, 0x100, v5
	v_bitop3_b32 v5, v139, v6, 15 bitop3:0x78
	v_or3_b32 v2, v2, v3, v8
	v_lshlrev_b32_e32 v3, 8, v140
	v_lshlrev_b32_e32 v5, 4, v5
	v_add_u32_e32 v142, s59, v2
	v_add3_u32 v143, v3, s0, v5
	v_and_or_b32 v3, s62, 32, v140
	s_add_i32 s59, s59, 0x8000
	s_add_i32 s66, s66, s3
	s_sub_i32 s26, s26, s28
	v_add_u32_e32 v152, s59, v2
	v_lshl_or_b32 v2, v3, 8, v4
	v_mov_b32_e32 v3, v1
	s_sub_i32 s68, s26, s66
	v_lshl_add_u64 v[136:137], s[6:7], 0, v[2:3]
	s_add_i32 s6, s68, 7
	s_ashr_i32 s7, s6, 31
	v_med3_i32 v2, s66, 4, v232
	s_lshl_b64 s[66:67], s[6:7], 12
	s_lshl_b32 s6, s28, 6
	s_waitcnt vmcnt(0)
	s_sub_i32 s59, s58, s6
	s_add_i32 s6, s68, 8
	v_mov_b32_e32 v16, v1
	v_mov_b32_e32 v17, v1
	v_cmp_gt_u32_e64 s[0:1], 32, v7
	v_lshl_add_u32 v146, v140, 2, s27
	v_add_u32_e32 v138, s27, v4
	v_readfirstlane_b32 s27, v2
	s_ashr_i32 s7, s6, 31
	v_mov_b32_e32 v2, v1
	v_mov_b32_e32 v4, v1
	v_mov_b32_e32 v5, v1
	v_mov_b32_e32 v6, v1
	v_mov_b32_e32 v7, v1
	v_mov_b32_e32 v8, v1
	v_mov_b32_e32 v9, v1
	v_mov_b32_e32 v10, v1
	v_mov_b32_e32 v11, v1
	v_mov_b32_e32 v12, v1
	v_mov_b32_e32 v13, v1
	v_mov_b32_e32 v14, v1
	v_mov_b32_e32 v15, v1
	v_mov_b64_e32 v[64:65], v[16:17]
	v_mov_b64_e32 v[48:49], v[16:17]
	v_mov_b64_e32 v[32:33], v[16:17]
	s_mov_b32 s4, 2
	v_lshlrev_b32_e32 v141, 2, v139
	v_xor_b32_e32 v144, 32, v143
	v_xor_b32_e32 v145, 64, v143
	v_xor_b32_e32 v147, 0x60, v143
	s_movk_i32 s5, 0x80
	v_xor_b32_e32 v148, 0x80, v143
	v_xor_b32_e32 v149, 0xa0, v143
	v_xor_b32_e32 v150, 0xc0, v143
	v_xor_b32_e32 v151, 0xe0, v143
	s_add_i32 s3, s27, -4
	s_add_i32 s27, s27, 4
	s_lshl_b64 s[68:69], s[6:7], 12
	v_mov_b32_e32 v153, 0
	v_mov_b32_e32 v155, 0xf149f2ca
	v_mov_b64_e32 v[62:63], v[14:15]
	v_mov_b64_e32 v[60:61], v[12:13]
	v_mov_b64_e32 v[58:59], v[10:11]
	v_mov_b64_e32 v[56:57], v[8:9]
	v_mov_b64_e32 v[54:55], v[6:7]
	v_mov_b64_e32 v[52:53], v[4:5]
	v_mov_b64_e32 v[50:51], v[2:3]
	v_mov_b64_e32 v[46:47], v[14:15]
	v_mov_b64_e32 v[44:45], v[12:13]
	v_mov_b64_e32 v[42:43], v[10:11]
	v_mov_b64_e32 v[40:41], v[8:9]
	v_mov_b64_e32 v[38:39], v[6:7]
	v_mov_b64_e32 v[36:37], v[4:5]
	v_mov_b64_e32 v[34:35], v[2:3]
	v_mov_b64_e32 v[30:31], v[14:15]
	v_mov_b64_e32 v[28:29], v[12:13]
	v_mov_b64_e32 v[26:27], v[10:11]
	v_mov_b64_e32 v[24:25], v[8:9]
	v_mov_b64_e32 v[22:23], v[6:7]
	v_mov_b64_e32 v[20:21], v[4:5]
	v_mov_b64_e32 v[18:19], v[2:3]
	s_waitcnt vmcnt(0) lgkmcnt(0)
	s_barrier
	s_cmp_lt_u32 s29, 0x2000
	s_cbranch_scc1 .Lna_l1_noprio
	s_setprio 1
.Lna_l1_noprio:
	s_branch .LBB0_1413
.LBB0_1411:
	s_or_b64 exec, exec, s[82:83]
	s_waitcnt lgkmcnt(0)
	ds_read_b128 v[160:163], v138 offset:224
	ds_read_b128 v[164:167], v138 offset:192
	ds_read_b128 v[168:171], v138 offset:160
	ds_read_b128 v[172:175], v138 offset:128
	s_waitcnt lgkmcnt(0)
	v_pk_mul_f32 v[16:17], v[16:17], v[162:163]
	v_pk_mul_f32 v[12:13], v[12:13], v[166:167]
	v_pk_mul_f32 v[8:9], v[8:9], v[170:171]
	v_pk_mul_f32 v[4:5], v[4:5], v[174:175]
	v_pk_mul_f32 v[14:15], v[14:15], v[160:161]
	v_pk_mul_f32 v[10:11], v[10:11], v[164:165]
	v_pk_mul_f32 v[6:7], v[6:7], v[168:169]
	v_pk_mul_f32 v[2:3], v[2:3], v[172:173]
	v_pk_mul_f32 v[64:65], v[64:65], v[162:163]
	v_pk_mul_f32 v[60:61], v[60:61], v[166:167]
	v_pk_mul_f32 v[56:57], v[56:57], v[170:171]
	v_pk_mul_f32 v[52:53], v[52:53], v[174:175]
	v_pk_mul_f32 v[62:63], v[62:63], v[160:161]
	v_pk_mul_f32 v[58:59], v[58:59], v[164:165]
	v_pk_mul_f32 v[54:55], v[54:55], v[168:169]
	v_pk_mul_f32 v[50:51], v[50:51], v[172:173]
	v_pk_mul_f32 v[48:49], v[48:49], v[162:163]
	v_pk_mul_f32 v[44:45], v[44:45], v[166:167]
	v_pk_mul_f32 v[40:41], v[40:41], v[170:171]
	v_pk_mul_f32 v[36:37], v[36:37], v[174:175]
	v_pk_mul_f32 v[46:47], v[46:47], v[160:161]
	v_pk_mul_f32 v[42:43], v[42:43], v[164:165]
	v_pk_mul_f32 v[38:39], v[38:39], v[168:169]
	v_pk_mul_f32 v[34:35], v[34:35], v[172:173]
	v_pk_mul_f32 v[32:33], v[32:33], v[162:163]
	v_pk_mul_f32 v[28:29], v[28:29], v[166:167]
	v_pk_mul_f32 v[24:25], v[24:25], v[170:171]
	v_pk_mul_f32 v[20:21], v[20:21], v[174:175]
	v_pk_mul_f32 v[30:31], v[30:31], v[160:161]
	v_pk_mul_f32 v[26:27], v[26:27], v[164:165]
	v_pk_mul_f32 v[22:23], v[22:23], v[168:169]
	v_pk_mul_f32 v[18:19], v[18:19], v[172:173]

; __device__ __forceinline__ int crow(int r, int hi) { return (r & 3) + 8 * (r >> 2) + 4 * hi; }
; template <bool NA> __device__ __forceinline__ void unit_body_v128(const Unit& U, char* lds) {
;     ...
;   if (hi == 0) li_l[r32] = l_reg; asm volatile("s_waitcnt lgkmcnt(0)" ::: "memory");
;   if (U.Of) {
;     float* Ow = U.Of + (long)(wid * QBLK) * LDO;
; #pragma unroll
;     for (int r = 0; r < 16; ++r) { const int orow = crow(r, hi); const float rl = __builtin_amdgcn_rcpf(li_l[orow]);
; #pragma unroll
;       for (int d0 = 0; d0 < 4; ++d0) Ow[(long)orow * LDO + d0 * 32 + r32] = o[d0][r] * rl; }
.LBB0_1426:
	s_setprio 0
	s_and_saveexec_b64 s[6:7], s[0:1]
	ds_write_b32 v146, v153
	s_or_b64 exec, exec, s[6:7]
	s_waitcnt lgkmcnt(0)
	ds_read_b32 v0, v138
	s_ashr_i32 s63, s62, 31
	s_cmp_eq_u64 s[18:19], 0
	s_waitcnt lgkmcnt(0)
	v_rcp_f32_e32 v0, v0
	s_nop 0
	v_mul_f32_e32 v68, v2, v0
	v_mul_f32_e32 v50, v50, v0
	v_mul_f32_e32 v34, v34, v0
	v_mul_f32_e32 v2, v18, v0
	s_cbranch_scc1 .LBB0_1447
; __device__ __forceinline__ int crow(int r, int hi) { return (r & 3) + 8 * (r >> 2) + 4 * hi; }
; template <bool NA> __device__ __forceinline__ void unit_body_v128(const Unit& U, char* lds) {
;     ...
;   if (U.Of) {
;     float* Ow = U.Of + (long)(wid * QBLK) * LDO;
; #pragma unroll
;     for (int r = 0; r < 16; ++r) { const int orow = crow(r, hi); const float rl = __builtin_amdgcn_rcpf(li_l[orow]);
; #pragma unroll
;       for (int d0 = 0; d0 < 4; ++d0) Ow[(long)orow * LDO + d0 * 32 + r32] = o[d0][r] * rl; }
	ds_read2_b32 v[72:73], v138 offset0:1 offset1:2
	s_lshl_b64 s[0:1], s[62:63], 13
	s_add_u32 s0, s18, s0
	s_addc_u32 s1, s19, s1
	v_lshlrev_b32_e32 v0, 2, v140
	s_waitcnt lgkmcnt(0)
	v_rcp_f32_e32 v69, v72
	v_lshl_add_u64 v[66:67], s[0:1], 0, v[0:1]
	v_lshlrev_b32_e32 v0, 15, v139
	v_lshlrev_b32_e32 v80, 13, v141
	v_lshl_add_u64 v[70:71], v[66:67], 0, v[0:1]
	v_or_b32_e32 v0, 0x2000, v80
	global_store_dword v[70:71], v68, off
	global_store_dword v[70:71], v50, off offset:128
	global_store_dword v[70:71], v34, off offset:256
	global_store_dword v[70:71], v2, off offset:384
	v_lshl_add_u64 v[70:71], v[66:67], 0, v[0:1]
	v_mul_f32_e32 v0, v3, v69
	global_store_dword v[70:71], v0, off
	v_mul_f32_e32 v0, v51, v69
	global_store_dword v[70:71], v0, off offset:128
	v_mul_f32_e32 v0, v35, v69
	global_store_dword v[70:71], v0, off offset:256
	v_mul_f32_e32 v0, v19, v69
	v_rcp_f32_e32 v69, v73
	ds_read_b32 v18, v138 offset:12
	global_store_dword v[70:71], v0, off offset:384
	v_or_b32_e32 v0, 0x4000, v80
	v_lshl_add_u64 v[70:71], v[66:67], 0, v[0:1]
	v_mul_f32_e32 v0, v4, v69
	global_store_dword v[70:71], v0, off
	v_mul_f32_e32 v0, v52, v69
	global_store_dword v[70:71], v0, off offset:128
	v_mul_f32_e32 v0, v36, v69
	global_store_dword v[70:71], v0, off offset:256
	v_mul_f32_e32 v0, v20, v69
	global_store_dword v[70:71], v0, off offset:384
	ds_read_b128 v[70:73], v138 offset:32
	s_waitcnt lgkmcnt(1)
	v_rcp_f32_e32 v18, v18
	v_or_b32_e32 v0, 0x6000, v80
	v_lshl_add_u64 v[78:79], v[66:67], 0, v[0:1]
	ds_read_b128 v[74:77], v138 offset:64
	v_mul_f32_e32 v0, v5, v18
	global_store_dword v[78:79], v0, off
	v_mul_f32_e32 v0, v53, v18
	global_store_dword v[78:79], v0, off offset:128
	v_mul_f32_e32 v0, v37, v18
	global_store_dword v[78:79], v0, off offset:256
	v_mul_f32_e32 v0, v21, v18
	s_waitcnt lgkmcnt(1)
	v_rcp_f32_e32 v18, v70
	global_store_dword v[78:79], v0, off offset:384
	v_or_b32_e32 v0, 0x10000, v80
	v_lshl_add_u64 v[78:79], v[66:67], 0, v[0:1]
	v_mul_f32_e32 v0, v6, v18
	global_store_dword v[78:79], v0, off
	v_mul_f32_e32 v0, v54, v18
	global_store_dword v[78:79], v0, off offset:128
	v_mul_f32_e32 v0, v38, v18
	global_store_dword v[78:79], v0, off offset:256
	v_mul_f32_e32 v0, v22, v18
	v_rcp_f32_e32 v18, v71
	global_store_dword v[78:79], v0, off offset:384
	v_or_b32_e32 v0, 0x12000, v80
	v_lshl_add_u64 v[70:71], v[66:67], 0, v[0:1]
	v_mul_f32_e32 v0, v7, v18
	global_store_dword v[70:71], v0, off
	v_mul_f32_e32 v0, v55, v18
	global_store_dword v[70:71], v0, off offset:128
	v_mul_f32_e32 v0, v39, v18
	global_store_dword v[70:71], v0, off offset:256
	v_mul_f32_e32 v0, v23, v18
	v_rcp_f32_e32 v18, v72
	global_store_dword v[70:71], v0, off offset:384
	v_or_b32_e32 v0, 0x14000, v80
	v_lshl_add_u64 v[70:71], v[66:67], 0, v[0:1]
	v_mul_f32_e32 v0, v8, v18
	global_store_dword v[70:71], v0, off
	v_mul_f32_e32 v0, v56, v18
	global_store_dword v[70:71], v0, off offset:128
	v_mul_f32_e32 v0, v40, v18
	global_store_dword v[70:71], v0, off offset:256
	v_mul_f32_e32 v0, v24, v18
	v_rcp_f32_e32 v18, v73
	global_store_dword v[70:71], v0, off offset:384
	v_or_b32_e32 v0, 0x16000, v80
	v_lshl_add_u64 v[70:71], v[66:67], 0, v[0:1]
	v_mul_f32_e32 v0, v9, v18
	global_store_dword v[70:71], v0, off
	v_mul_f32_e32 v0, v57, v18
	global_store_dword v[70:71], v0, off offset:128
	v_mul_f32_e32 v0, v41, v18
	global_store_dword v[70:71], v0, off offset:256
	v_mul_f32_e32 v0, v25, v18
	s_waitcnt lgkmcnt(0)
	v_rcp_f32_e32 v18, v74
	global_store_dword v[70:71], v0, off offset:384
	v_or_b32_e32 v0, 0x20000, v80
	v_lshl_add_u64 v[70:71], v[66:67], 0, v[0:1]
	v_mul_f32_e32 v0, v10, v18
	global_store_dword v[70:71], v0, off
	v_mul_f32_e32 v0, v58, v18
	global_store_dword v[70:71], v0, off offset:128
	v_mul_f32_e32 v0, v42, v18
	global_store_dword v[70:71], v0, off offset:256
	v_mul_f32_e32 v0, v26, v18
	v_rcp_f32_e32 v18, v75
	global_store_dword v[70:71], v0, off offset:384
	v_or_b32_e32 v0, 0x22000, v80
	v_lshl_add_u64 v[70:71], v[66:67], 0, v[0:1]
	v_mul_f32_e32 v0, v11, v18
	global_store_dword v[70:71], v0, off
	v_mul_f32_e32 v0, v59, v18
	global_store_dword v[70:71], v0, off offset:128
	v_mul_f32_e32 v0, v43, v18
	global_store_dword v[70:71], v0, off offset:256
	v_mul_f32_e32 v0, v27, v18
	v_rcp_f32_e32 v18, v76
	global_store_dword v[70:71], v0, off offset:384
	v_or_b32_e32 v0, 0x24000, v80
	v_lshl_add_u64 v[70:71], v[66:67], 0, v[0:1]
	v_mul_f32_e32 v0, v12, v18
	global_store_dword v[70:71], v0, off
	v_mul_f32_e32 v0, v60, v18
	global_store_dword v[70:71], v0, off offset:128
	v_mul_f32_e32 v0, v44, v18
	global_store_dword v[70:71], v0, off offset:256
	v_mul_f32_e32 v0, v28, v18
	v_rcp_f32_e32 v18, v77
	global_store_dword v[70:71], v0, off offset:384
	ds_read_b128 v[70:73], v138 offset:96
	v_or_b32_e32 v0, 0x26000, v80
	v_lshl_add_u64 v[74:75], v[66:67], 0, v[0:1]
	v_mul_f32_e32 v0, v13, v18
	global_store_dword v[74:75], v0, off
	v_mul_f32_e32 v0, v61, v18
	global_store_dword v[74:75], v0, off offset:128
	v_mul_f32_e32 v0, v45, v18
	global_store_dword v[74:75], v0, off offset:256
	v_mul_f32_e32 v0, v29, v18
	s_waitcnt lgkmcnt(0)
	v_rcp_f32_e32 v18, v70
	global_store_dword v[74:75], v0, off offset:384
	v_or_b32_e32 v0, 0x30000, v80
	v_lshl_add_u64 v[74:75], v[66:67], 0, v[0:1]
	v_mul_f32_e32 v0, v14, v18
	global_store_dword v[74:75], v0, off
	v_mul_f32_e32 v0, v62, v18
	global_store_dword v[74:75], v0, off offset:128
	v_mul_f32_e32 v0, v46, v18
	global_store_dword v[74:75], v0, off offset:256
	v_mul_f32_e32 v0, v30, v18
	v_rcp_f32_e32 v18, v71
	global_store_dword v[74:75], v0, off offset:384
	v_or_b32_e32 v0, 0x32000, v80
	v_lshl_add_u64 v[70:71], v[66:67], 0, v[0:1]
	v_mul_f32_e32 v0, v15, v18
	global_store_dword v[70:71], v0, off
	v_mul_f32_e32 v0, v63, v18
	global_store_dword v[70:71], v0, off offset:128
	v_mul_f32_e32 v0, v47, v18
	global_store_dword v[70:71], v0, off offset:256
	v_mul_f32_e32 v0, v31, v18
	v_rcp_f32_e32 v18, v72
	global_store_dword v[70:71], v0, off offset:384
	v_or_b32_e32 v0, 0x34000, v80
	v_lshl_add_u64 v[70:71], v[66:67], 0, v[0:1]
	v_mul_f32_e32 v0, v16, v18
	global_store_dword v[70:71], v0, off
	v_mul_f32_e32 v0, v64, v18
	global_store_dword v[70:71], v0, off offset:128
	v_mul_f32_e32 v0, v48, v18
	global_store_dword v[70:71], v0, off offset:256
	v_mul_f32_e32 v0, v32, v18
	v_rcp_f32_e32 v18, v73
	global_store_dword v[70:71], v0, off offset:384
	v_or_b32_e32 v0, 0x36000, v80
	v_lshl_add_u64 v[66:67], v[66:67], 0, v[0:1]
	v_mul_f32_e32 v0, v17, v18
	global_store_dword v[66:67], v0, off
	v_mul_f32_e32 v0, v65, v18
	global_store_dword v[66:67], v0, off offset:128
	v_mul_f32_e32 v0, v49, v18
	global_store_dword v[66:67], v0, off offset:256
	v_mul_f32_e32 v0, v33, v18
	global_store_dword v[66:67], v0, off offset:384
	s_cbranch_execnz .LBB0_1431
